# NSA top-k: bisection step with the four query chains interleaved + SALU loop control, importance reads batched (on top of window-loop rewrite and item-loop in-place prefetch)
# speedup vs baseline: 1.0065x; 1.0026x over previous
.LBB0_1314:
	s_or_b32 s26, s4, s84
	v_lshl_add_u32 v13, s26, 9, v1
	v_mov_b32_e32 v3, 1
	v_mov_b32_e32 v2, 1
	v_mov_b32_e32 v6, 1
	v_mov_b32_e32 v7, 1
	v_mov_b32_e32 v4, 1
	v_mov_b32_e32 v5, 1
	v_mov_b32_e32 v10, 1
	v_mov_b32_e32 v11, 1
	s_and_saveexec_b64 s[24:25], s[18:19]
	ds_read_b32 v14, v13 offset:43008
	ds_read_b32 v15, v13 offset:43520
	ds_read_b32 v16, v13 offset:44032
	ds_read_b32 v17, v13 offset:44544
	s_or_b64 exec, exec, s[24:25]
	s_and_saveexec_b64 s[24:25], s[22:23]
	ds_read_b32 v18, v13 offset:43264
	ds_read_b32 v19, v13 offset:43776
	ds_read_b32 v20, v13 offset:44288
	ds_read_b32 v21, v13 offset:44800
	s_or_b64 exec, exec, s[24:25]
	s_waitcnt lgkmcnt(0)
	s_and_saveexec_b64 s[24:25], s[18:19]
	v_add_u32_e32 v3, 1, v14
	v_add_u32_e32 v6, 1, v15
	v_add_u32_e32 v4, 1, v16
	v_add_u32_e32 v10, 1, v17
	s_or_b64 exec, exec, s[24:25]
	s_and_saveexec_b64 s[24:25], s[22:23]
	v_add_u32_e32 v2, 1, v18
	v_add_u32_e32 v7, 1, v19
	v_add_u32_e32 v5, 1, v20
	v_add_u32_e32 v11, 1, v21
	s_or_b64 exec, exec, s[24:25]
	v_cndmask_b32_e64 v3, v3, v221, s[12:13]
	v_cndmask_b32_e64 v2, v2, v221, s[14:15]
	v_cndmask_b32_e64 v4, v4, v221, s[12:13]
	v_cndmask_b32_e64 v5, v5, v221, s[14:15]
	v_cndmask_b32_e64 v6, v6, v221, s[12:13]
	v_cndmask_b32_e64 v7, v7, v221, s[14:15]
	v_cndmask_b32_e64 v8, v3, 0, s[16:17]
	v_cndmask_b32_e64 v9, v2, 0, s[20:21]
	v_cndmask_b32_e64 v2, v10, v221, s[12:13]
	v_cndmask_b32_e64 v3, v11, v221, s[14:15]
	v_cndmask_b32_e64 v4, v4, 0, s[16:17]
	v_cndmask_b32_e64 v5, v5, 0, s[20:21]
	v_cndmask_b32_e64 v6, v6, 0, s[16:17]
	v_cndmask_b32_e64 v7, v7, 0, s[20:21]
	v_cndmask_b32_e64 v2, v2, 0, s[16:17]
	v_cndmask_b32_e64 v3, v3, 0, s[20:21]
	s_mov_b32 s97, 1
	s_andn2_b64 vcc, exec, s[46:47]
	s_mov_b32 s74, 1
	s_mov_b32 s75, 1
	s_mov_b32 s54, 1
	s_cbranch_vccnz .LBB0_1333
	s_mov_b32 s50, 30
	s_mov_b32 s54, 0
	s_mov_b32 s75, 0
	s_mov_b32 s74, 0
	s_mov_b32 s97, 0
	s_mov_b32 s51, 0
.LBB0_1332:
	s_lshl_b32 s55, 1, s50
	s_or_b32 s32, s55, s54
	s_or_b32 s58, s55, s75
	s_or_b32 s59, s55, s74
	s_or_b32 s60, s55, s97
	v_cmp_le_u32_e32 vcc, s32, v8
	v_cmp_le_u32_e64 s[4:5], s32, v9
	v_cmp_le_u32_e64 s[24:25], s58, v6
	v_cmp_le_u32_e64 s[56:57], s58, v7
	v_cmp_le_u32_e64 s[98:99], s59, v4
	v_cmp_le_u32_e64 s[100:101], s59, v5
	s_bcnt1_i32_b64 s61, vcc
	s_bcnt1_i32_b64 s4, s[4:5]
	s_add_i32 s61, s61, s4
	v_cmp_le_u32_e32 vcc, s60, v2
	v_cmp_le_u32_e64 s[4:5], s60, v3
	s_cmp_gt_u32 s61, 15
	s_cselect_b32 s54, s32, s54
	s_cmp_eq_u32 s61, 16
	s_cselect_b32 s61, 1, 0
	s_or_b32 s51, s51, s61
	s_bcnt1_i32_b64 s24, s[24:25]
	s_bcnt1_i32_b64 s56, s[56:57]
	s_add_i32 s24, s24, s56
	s_cmp_gt_u32 s24, 15
	s_cselect_b32 s75, s58, s75
	s_cmp_eq_u32 s24, 16
	s_cselect_b32 s24, 2, 0
	s_or_b32 s51, s51, s24
	s_bcnt1_i32_b64 s98, s[98:99]
	s_bcnt1_i32_b64 s100, s[100:101]
	s_add_i32 s98, s98, s100
	s_cmp_gt_u32 s98, 15
	s_cselect_b32 s74, s59, s74
	s_cmp_eq_u32 s98, 16
	s_cselect_b32 s98, 4, 0
	s_or_b32 s51, s51, s98
	s_bcnt1_i32_b64 s61, vcc
	s_bcnt1_i32_b64 s4, s[4:5]
	s_add_i32 s61, s61, s4
	s_cmp_gt_u32 s61, 15
	s_cselect_b32 s97, s60, s97
	s_cmp_eq_u32 s61, 16
	s_cselect_b32 s61, 8, 0
	s_or_b32 s51, s51, s61
	s_add_i32 s50, s50, -1
	s_cmp_lg_u32 s51, 15
	s_cselect_b32 s61, 1, 0
	s_cmp_gt_i32 s50, -1
	s_cselect_b32 s4, 1, 0
	s_and_b32 s4, s4, s61
	s_cmp_lg_u32 s4, 0
	s_cbranch_scc1 .LBB0_1332

	.amdhsa_kernel _Z10fwd_kernel4Args
		.amdhsa_group_segment_fixed_size 0
		.amdhsa_private_segment_fixed_size 0
		.amdhsa_kernarg_size 440
		.amdhsa_user_sgpr_count 2
		.amdhsa_user_sgpr_dispatch_ptr 0
		.amdhsa_user_sgpr_queue_ptr 0
		.amdhsa_user_sgpr_kernarg_segment_ptr 1
		.amdhsa_user_sgpr_dispatch_id 0
		.amdhsa_user_sgpr_kernarg_preload_length 0
		.amdhsa_user_sgpr_kernarg_preload_offset 0
		.amdhsa_user_sgpr_private_segment_size 0
		.amdhsa_uses_dynamic_stack 0
		.amdhsa_enable_private_segment 0
		.amdhsa_system_sgpr_workgroup_id_x 1
		.amdhsa_system_sgpr_workgroup_id_y 0
		.amdhsa_system_sgpr_workgroup_id_z 0
		.amdhsa_system_sgpr_workgroup_info 0
		.amdhsa_system_vgpr_workitem_id 0
		.amdhsa_next_free_vgpr 251
		.amdhsa_next_free_sgpr 102
		.amdhsa_accum_offset 252
		.amdhsa_reserve_vcc 1
		.amdhsa_float_round_mode_32 0
		.amdhsa_float_round_mode_16_64 0
		.amdhsa_float_denorm_mode_32 3
		.amdhsa_float_denorm_mode_16_64 3
		.amdhsa_dx10_clamp 1
		.amdhsa_ieee_mode 1
		.amdhsa_fp16_overflow 0
		.amdhsa_tg_split 0
		.amdhsa_exception_fp_ieee_invalid_op 0
		.amdhsa_exception_fp_denorm_src 0
		.amdhsa_exception_fp_ieee_div_zero 0
		.amdhsa_exception_fp_ieee_overflow 0
		.amdhsa_exception_fp_ieee_underflow 0
		.amdhsa_exception_fp_ieee_inexact 0
		.amdhsa_exception_int_div_zero 0
	.end_amdhsa_kernel

amdhsa.kernels:
  - .agpr_count:     0
    .args:
      - .offset:         0
        .size:           184
        .value_kind:     by_value
      - .offset:         184
        .size:           4
        .value_kind:     hidden_block_count_x
      - .offset:         188
        .size:           4
        .value_kind:     hidden_block_count_y
      - .offset:         192
        .size:           4
        .value_kind:     hidden_block_count_z
      - .offset:         196
        .size:           2
        .value_kind:     hidden_group_size_x
      - .offset:         198
        .size:           2
        .value_kind:     hidden_group_size_y
      - .offset:         200
        .size:           2
        .value_kind:     hidden_group_size_z
      - .offset:         202
        .size:           2
        .value_kind:     hidden_remainder_x
      - .offset:         204
        .size:           2
        .value_kind:     hidden_remainder_y
      - .offset:         206
        .size:           2
        .value_kind:     hidden_remainder_z
      - .offset:         224
        .size:           8
        .value_kind:     hidden_global_offset_x
      - .offset:         232
        .size:           8
        .value_kind:     hidden_global_offset_y
      - .offset:         240
        .size:           8
        .value_kind:     hidden_global_offset_z
      - .offset:         248
        .size:           2
        .value_kind:     hidden_grid_dims
      - .offset:         304
        .size:           4
        .value_kind:     hidden_dynamic_lds_size
    .group_segment_fixed_size: 0
    .kernarg_segment_align: 8
    .kernarg_segment_size: 440
    .language:       OpenCL C
    .language_version:
      - 2
      - 0
    .max_flat_workgroup_size: 512
    .name:           _Z10fwd_kernel4Args
    .private_segment_fixed_size: 0
    .sgpr_count:     108
    .sgpr_spill_count: 4
    .symbol:         _Z10fwd_kernel4Args.kd
    .uniform_work_group_size: 1
    .uses_dynamic_stack: false
    .vgpr_count:     251
    .vgpr_spill_count: 0
    .wavefront_size: 64
